# v31: v30 + phase-1 norm loop: next 4 rows software-prefetched one iteration ahead into spare VGPRs (counted vmcnt)
# speedup vs baseline: 1.0156x; 1.0156x over previous
.Lp1_top:
	s_mov_b64 s[4:5], s[0:1]
	s_mov_b32 s6, 0
	s_and_b32 s7, s33, 0xffffffc0
	v_mbcnt_lo_u32_b32 v0, -1, s6
	v_mbcnt_hi_u32_b32 v0, -1, v0
	v_or_b32_e32 v103, s7, v0
	v_mbcnt_lo_u32_b32 v0, -1, 0
	v_mbcnt_hi_u32_b32 v0, -1, v0
	v_and_b32_e32 v1, 64, v0
	v_add_u32_e32 v1, 64, v1
	v_xor_b32_e32 v2, 1, v0
	v_cmp_lt_i32_e32 vcc, v2, v1
	v_mov_b32_e32 v97, 0
	v_and_b32_e32 v102, 63, v103
	v_cndmask_b32_e32 v2, v0, v2, vcc
	v_lshlrev_b32_e32 v109, 2, v2
	v_xor_b32_e32 v2, 2, v0
	v_cmp_lt_i32_e32 vcc, v2, v1
	v_lshlrev_b32_e32 v96, 3, v102
	s_load_dword s44, s[0:1], 0xb8
	s_load_dwordx2 s[38:39], s[4:5], 0xa0
	s_load_dwordx4 s[28:31], s[4:5], 0x0
	s_load_dwordx2 s[6:7], s[4:5], 0x20
	s_load_dwordx2 s[26:27], s[4:5], 0x70
	s_load_dwordx4 s[20:23], s[4:5], 0x60
	s_load_dwordx8 s[8:15], s[4:5], 0x40
	v_cndmask_b32_e32 v2, v0, v2, vcc
	v_lshlrev_b32_e32 v108, 2, v2
	v_xor_b32_e32 v2, 4, v0
	v_cmp_lt_i32_e32 vcc, v2, v1
	s_mov_b64 s[4:5], 0xe800000
	s_waitcnt lgkmcnt(0)
	s_add_u32 s45, s38, 0x100000
	v_cndmask_b32_e32 v2, v0, v2, vcc
	v_lshlrev_b32_e32 v107, 2, v2
	v_xor_b32_e32 v2, 8, v0
	v_cmp_lt_i32_e32 vcc, v2, v1
	s_mov_b32 s41, 0
	s_mov_b32 s51, -1
	v_cndmask_b32_e32 v2, v0, v2, vcc
	v_lshlrev_b32_e32 v106, 2, v2
	v_xor_b32_e32 v2, 16, v0
	v_cmp_lt_i32_e32 vcc, v2, v1
	s_addc_u32 s46, s39, 0
	s_add_i32 s47, s61, s62
	v_cndmask_b32_e32 v2, v0, v2, vcc
	v_lshlrev_b32_e32 v105, 2, v2
	v_xor_b32_e32 v2, 32, v0
	v_cmp_lt_i32_e32 vcc, v2, v1
	v_mov_b32_e32 v110, 0x358637bd
	s_mov_b32 s48, 0xf800000
	v_cndmask_b32_e32 v0, v0, v2, vcc
	v_lshlrev_b32_e32 v104, 2, v0
	v_lshl_add_u64 v[0:1], s[38:39], 0, v[96:97]
	v_lshl_add_u64 v[98:99], v[0:1], 0, s[4:5]
	v_lshlrev_b32_e32 v0, 5, v102
	v_mov_b32_e32 v1, v97
	v_lshl_add_u64 v[100:101], s[6:7], 0, v[0:1]
	v_or_b32_e32 v0, 0x200, v96
	v_lshlrev_b32_e32 v97, 2, v0
	v_mov_b32_e32 v111, 0x260
	s_mov_b32 s49, 0xc3e00000
	v_lshlrev_b32_e32 v112, 2, v96
	v_mov_b32_e32 v113, 0x43e00000
	s_mov_b32 s50, 0
	s_cmp_eq_u32 s98, 1
	s_cbranch_scc1 .LBB0_75
	s_add_i32 s100, s47, s50
	s_mov_b32 s101, 0
	s_cmpk_gt_i32 s100, 0x7fff
	s_cbranch_scc1 .Lnp_xs0
	s_lshl_b64 s[6:7], s[100:101], 12
	s_add_u32 s6, s28, s6
	s_addc_u32 s7, s29, s7
	s_branch .Lnp_go0
.Lnp_xs0:
	s_add_i32 s100, s100, 0xffff8000
	s_lshl_b64 s[6:7], s[100:101], 12
	s_add_u32 s6, s30, s6
	s_addc_u32 s7, s31, s7
.Lnp_go0:
	global_load_dwordx4 v[140:143], v112, s[6:7] nt
	global_load_dwordx4 v[144:147], v112, s[6:7] offset:16 nt
	global_load_dwordx4 v[148:151], v112, s[6:7] offset:2064 nt
	global_load_dwordx4 v[152:155], v112, s[6:7] offset:2048 nt
	s_add_u32 s100, s6, 0x1000
	s_addc_u32 s101, s7, 0
	global_load_dwordx4 v[156:159], v112, s[100:101] nt
	global_load_dwordx4 v[160:163], v112, s[100:101] offset:16 nt
	global_load_dwordx4 v[164:167], v97, s[100:101] offset:16 nt
	global_load_dwordx4 v[168:171], v97, s[100:101] nt
	s_add_u32 s100, s6, 0x2000
	s_addc_u32 s101, s7, 0
	global_load_dwordx4 v[172:175], v112, s[100:101] nt
	global_load_dwordx4 v[176:179], v112, s[100:101] offset:16 nt
	global_load_dwordx4 v[180:183], v97, s[100:101] offset:16 nt
	global_load_dwordx4 v[184:187], v97, s[100:101] nt
	s_add_u32 s100, s6, 0x3000
	s_addc_u32 s101, s7, 0
	global_load_dwordx4 v[188:191], v112, s[100:101] offset:16 nt
	global_load_dwordx4 v[192:195], v112, s[100:101] nt
	global_load_dwordx4 v[196:199], v97, s[100:101] nt
	global_load_dwordx4 v[200:203], v97, s[100:101] offset:16 nt
	s_branch .LBB0_69
.LBB0_68:
	s_waitcnt vmcnt(8)
	v_mov_b64_e32 v[92:93], v[140:141]
	v_mov_b64_e32 v[94:95], v[142:143]
	v_mov_b64_e32 v[88:89], v[144:145]
	v_mov_b64_e32 v[90:91], v[146:147]
	v_mov_b64_e32 v[80:81], v[148:149]
	v_mov_b64_e32 v[82:83], v[150:151]
	v_mov_b64_e32 v[84:85], v[152:153]
	v_mov_b64_e32 v[86:87], v[154:155]
	v_mov_b64_e32 v[76:77], v[156:157]
	v_mov_b64_e32 v[78:79], v[158:159]
	v_mov_b64_e32 v[72:73], v[160:161]
	v_mov_b64_e32 v[74:75], v[162:163]
	v_mov_b64_e32 v[64:65], v[164:165]
	v_mov_b64_e32 v[66:67], v[166:167]
	v_mov_b64_e32 v[68:69], v[168:169]
	v_mov_b64_e32 v[70:71], v[170:171]
	v_mov_b64_e32 v[60:61], v[172:173]
	v_mov_b64_e32 v[62:63], v[174:175]
	v_mov_b64_e32 v[56:57], v[176:177]
	v_mov_b64_e32 v[58:59], v[178:179]
	v_mov_b64_e32 v[48:49], v[180:181]
	v_mov_b64_e32 v[50:51], v[182:183]
	v_mov_b64_e32 v[52:53], v[184:185]
	v_mov_b64_e32 v[54:55], v[186:187]
	v_mov_b64_e32 v[40:41], v[188:189]
	v_mov_b64_e32 v[42:43], v[190:191]
	v_mov_b64_e32 v[44:45], v[192:193]
	v_mov_b64_e32 v[46:47], v[194:195]
	v_mov_b64_e32 v[36:37], v[196:197]
	v_mov_b64_e32 v[38:39], v[198:199]
	v_mov_b64_e32 v[32:33], v[200:201]
	v_mov_b64_e32 v[34:35], v[202:203]
	s_add_i32 s50, s50, 4
	s_cmp_eq_u32 s50, 24
	s_cbranch_scc1 .Lnp_skip
	s_add_i32 s100, s47, s50
	s_mov_b32 s101, 0
	s_cmpk_gt_i32 s100, 0x7fff
	s_cbranch_scc1 .Lnp_xs1
	s_lshl_b64 s[6:7], s[100:101], 12
	s_add_u32 s6, s28, s6
	s_addc_u32 s7, s29, s7
	s_branch .Lnp_go1

.Lnp_go1:
	global_load_dwordx4 v[140:143], v112, s[6:7] nt
	global_load_dwordx4 v[144:147], v112, s[6:7] offset:16 nt
	global_load_dwordx4 v[148:151], v112, s[6:7] offset:2064 nt
	global_load_dwordx4 v[152:155], v112, s[6:7] offset:2048 nt
	s_add_u32 s100, s6, 0x1000
	s_addc_u32 s101, s7, 0
	global_load_dwordx4 v[156:159], v112, s[100:101] nt
	global_load_dwordx4 v[160:163], v112, s[100:101] offset:16 nt
	global_load_dwordx4 v[164:167], v97, s[100:101] offset:16 nt
	global_load_dwordx4 v[168:171], v97, s[100:101] nt
	s_add_u32 s100, s6, 0x2000
	s_addc_u32 s101, s7, 0
	global_load_dwordx4 v[172:175], v112, s[100:101] nt
	global_load_dwordx4 v[176:179], v112, s[100:101] offset:16 nt
	global_load_dwordx4 v[180:183], v97, s[100:101] offset:16 nt
	global_load_dwordx4 v[184:187], v97, s[100:101] nt
	s_add_u32 s100, s6, 0x3000
	s_addc_u32 s101, s7, 0
	global_load_dwordx4 v[188:191], v112, s[100:101] offset:16 nt
	global_load_dwordx4 v[192:195], v112, s[100:101] nt
	global_load_dwordx4 v[196:199], v97, s[100:101] nt
	global_load_dwordx4 v[200:203], v97, s[100:101] offset:16 nt
.Lnp_skip:
	v_pk_mul_f32 v[114:115], v[94:95], v[94:95]
	v_pk_mul_f32 v[116:117], v[92:93], v[92:93]
	v_pk_mul_f32 v[118:119], v[90:91], v[90:91]
	v_pk_mul_f32 v[120:121], v[88:89], v[88:89]
	v_mul_f32_e32 v125, v82, v82
	v_mul_f32_e32 v122, v85, v85
	v_mul_f32_e32 v124, v87, v87
	v_mul_f32_e32 v128, v83, v83
	v_pk_mov_b32 v[126:127], v[116:117], v[114:115] op_sel:[1,0]
	v_mov_b32_e32 v117, v115
	v_pk_mov_b32 v[114:115], v[120:121], v[118:119] op_sel:[1,0]
	v_mov_b32_e32 v121, v119
	v_pk_fma_f32 v[118:119], v[84:85], v[84:85], v[122:123] op_sel_hi:[1,1,0]
	v_pk_fma_f32 v[122:123], v[86:87], v[86:87], v[124:125] op_sel_hi:[1,1,0]
	v_pk_add_f32 v[116:117], v[126:127], v[116:117]
	v_pk_add_f32 v[114:115], v[114:115], v[120:121]
	v_mov_b32_e32 v119, v125
	v_mov_b32_e32 v123, v128
	v_pk_mul_f32 v[120:121], v[78:79], v[78:79]
	v_pk_mul_f32 v[124:125], v[76:77], v[76:77]
	v_pk_mul_f32 v[126:127], v[74:75], v[74:75]
	v_pk_mul_f32 v[128:129], v[72:73], v[72:73]
	v_mul_f32_e32 v133, v80, v80
	v_mul_f32_e32 v134, v81, v81
	v_mul_f32_e32 v130, v69, v69
	v_mul_f32_e32 v132, v71, v71
	v_pk_add_f32 v[116:117], v[116:117], v[116:117] op_sel:[0,1] op_sel_hi:[1,0]
	v_pk_add_f32 v[114:115], v[114:115], v[114:115] op_sel:[0,1] op_sel_hi:[1,0]
	v_pk_add_f32 v[118:119], v[118:119], v[122:123]
	v_pk_mov_b32 v[122:123], v[124:125], v[120:121] op_sel:[1,0]
	v_mov_b32_e32 v125, v121
	v_pk_mov_b32 v[120:121], v[128:129], v[126:127] op_sel:[1,0]
	v_mov_b32_e32 v129, v127
	v_mul_f32_e32 v135, v66, v66
	v_mul_f32_e32 v138, v67, v67
	v_pk_fma_f32 v[126:127], v[68:69], v[68:69], v[130:131] op_sel_hi:[1,1,0]
	v_pk_fma_f32 v[130:131], v[70:71], v[70:71], v[132:133] op_sel_hi:[1,1,0]
	v_mov_b32_e32 v117, v133
	v_mov_b32_e32 v115, v134
	v_pk_add_f32 v[122:123], v[122:123], v[124:125]
	v_pk_add_f32 v[120:121], v[120:121], v[128:129]
	v_mul_f32_e32 v136, v64, v64
	v_mul_f32_e32 v137, v65, v65
	v_mov_b32_e32 v127, v135
	v_mov_b32_e32 v131, v138
	v_pk_mul_f32 v[124:125], v[62:63], v[62:63]
	v_pk_mul_f32 v[128:129], v[60:61], v[60:61]
	v_pk_add_f32 v[114:115], v[116:117], v[114:115]
	v_pk_add_f32 v[116:117], v[122:123], v[122:123] op_sel:[0,1] op_sel_hi:[1,0]
	v_pk_add_f32 v[120:121], v[120:121], v[120:121] op_sel:[0,1] op_sel_hi:[1,0]
	v_pk_mul_f32 v[132:133], v[58:59], v[58:59]
	v_pk_mul_f32 v[134:135], v[56:57], v[56:57]
	v_pk_add_f32 v[122:123], v[126:127], v[130:131]
	v_pk_mov_b32 v[126:127], v[128:129], v[124:125] op_sel:[1,0]
	v_mov_b32_e32 v129, v125
	v_pk_add_f32 v[114:115], v[114:115], v[118:119]
	v_mov_b32_e32 v117, v136
	v_mov_b32_e32 v121, v137
	v_pk_mov_b32 v[124:125], v[134:135], v[132:133] op_sel:[1,0]
	v_mov_b32_e32 v135, v133
	v_pk_add_f32 v[118:119], v[126:127], v[128:129]
	v_add_f32_e32 v126, v114, v115
	v_pk_add_f32 v[114:115], v[116:117], v[120:121]
	v_pk_add_f32 v[124:125], v[124:125], v[134:135]
	v_pk_add_f32 v[114:115], v[114:115], v[122:123]
	v_mul_f32_e32 v138, v48, v48
	v_mul_f32_e32 v139, v49, v49
	v_add_f32_e32 v122, v114, v115
	v_pk_add_f32 v[114:115], v[118:119], v[118:119] op_sel:[0,1] op_sel_hi:[1,0]
	v_pk_add_f32 v[116:117], v[124:125], v[124:125] op_sel:[0,1] op_sel_hi:[1,0]
	v_mov_b32_e32 v115, v138
	v_mov_b32_e32 v117, v139
	v_pk_add_f32 v[114:115], v[114:115], v[116:117]
	v_mul_f32_e32 v116, v53, v53
	v_mul_f32_e32 v118, v55, v55
	v_mul_f32_e32 v120, v50, v50
	v_mul_f32_e32 v121, v51, v51
	v_pk_fma_f32 v[116:117], v[52:53], v[52:53], v[116:117] op_sel_hi:[1,1,0]
	v_pk_fma_f32 v[118:119], v[54:55], v[54:55], v[118:119] op_sel_hi:[1,1,0]
	v_mov_b32_e32 v117, v120
	v_mov_b32_e32 v119, v121
	v_pk_add_f32 v[116:117], v[116:117], v[118:119]
	s_nop 0
	v_pk_add_f32 v[114:115], v[114:115], v[116:117]
	v_pk_mul_f32 v[116:117], v[44:45], v[44:45]
	v_add_f32_e32 v123, v114, v115
	v_pk_mul_f32 v[114:115], v[46:47], v[46:47]
	s_nop 0
	v_pk_mov_b32 v[118:119], v[116:117], v[114:115] op_sel:[1,0]
	v_mov_b32_e32 v117, v115
	v_pk_add_f32 v[114:115], v[118:119], v[116:117]
	v_pk_mul_f32 v[116:117], v[42:43], v[42:43]
	v_pk_mul_f32 v[118:119], v[40:41], v[40:41]
	v_pk_add_f32 v[114:115], v[114:115], v[114:115] op_sel:[0,1] op_sel_hi:[1,0]
	v_pk_mov_b32 v[120:121], v[118:119], v[116:117] op_sel:[1,0]
	v_mov_b32_e32 v119, v117
	v_pk_add_f32 v[116:117], v[120:121], v[118:119]
	v_mul_f32_e32 v118, v32, v32
	v_mul_f32_e32 v119, v33, v33
	v_pk_add_f32 v[116:117], v[116:117], v[116:117] op_sel:[0,1] op_sel_hi:[1,0]
	v_mov_b32_e32 v115, v118
	v_mov_b32_e32 v117, v119
	v_pk_add_f32 v[114:115], v[114:115], v[116:117]
	v_mul_f32_e32 v116, v37, v37
	v_mul_f32_e32 v120, v34, v34
	v_pk_fma_f32 v[116:117], v[36:37], v[36:37], v[116:117] op_sel_hi:[1,1,0]
	v_mul_f32_e32 v118, v39, v39
	v_mov_b32_e32 v117, v120
	ds_bpermute_b32 v120, v109, v126
	v_mul_f32_e32 v121, v35, v35
	v_pk_fma_f32 v[118:119], v[38:39], v[38:39], v[118:119] op_sel_hi:[1,1,0]
	s_nop 0
	v_mov_b32_e32 v119, v121
	v_pk_add_f32 v[116:117], v[116:117], v[118:119]
	s_nop 0
	v_pk_add_f32 v[114:115], v[114:115], v[116:117]
	ds_bpermute_b32 v116, v109, v122
	v_add_f32_e32 v114, v114, v115
	s_waitcnt lgkmcnt(1)
	v_add_f32_e32 v115, v126, v120
	ds_bpermute_b32 v119, v108, v115
	ds_bpermute_b32 v118, v109, v114
	s_waitcnt lgkmcnt(2)
	v_add_f32_e32 v116, v122, v116
	ds_bpermute_b32 v117, v109, v123
	s_waitcnt lgkmcnt(2)
	v_add_f32_e32 v115, v115, v119
	ds_bpermute_b32 v121, v107, v115
	s_waitcnt lgkmcnt(2)
	v_add_f32_e32 v114, v114, v118
	ds_bpermute_b32 v118, v108, v116
	s_waitcnt lgkmcnt(2)
	v_add_f32_e32 v117, v123, v117
	ds_bpermute_b32 v119, v108, v117
	s_waitcnt lgkmcnt(2)
	v_add_f32_e32 v115, v115, v121
	ds_bpermute_b32 v121, v106, v115
	s_waitcnt lgkmcnt(2)
	v_add_f32_e32 v116, v116, v118
	ds_bpermute_b32 v118, v107, v116
	ds_bpermute_b32 v120, v108, v114
	s_waitcnt lgkmcnt(3)
	v_add_f32_e32 v117, v117, v119
	s_waitcnt lgkmcnt(2)
	v_add_f32_e32 v115, v115, v121
	ds_bpermute_b32 v121, v105, v115
	s_waitcnt lgkmcnt(2)
	v_add_f32_e32 v116, v116, v118
	ds_bpermute_b32 v118, v106, v116
	s_waitcnt lgkmcnt(2)
	v_add_f32_e32 v114, v114, v120
	ds_bpermute_b32 v119, v107, v117
	s_waitcnt lgkmcnt(2)
	v_add_f32_e32 v115, v115, v121
	ds_bpermute_b32 v121, v104, v115
	s_waitcnt lgkmcnt(2)
	v_add_f32_e32 v116, v116, v118
	ds_bpermute_b32 v118, v105, v116
	ds_bpermute_b32 v120, v107, v114
	s_waitcnt lgkmcnt(3)
	v_add_f32_e32 v117, v117, v119
	s_waitcnt lgkmcnt(2)
	v_add_f32_e32 v115, v115, v121
	v_fmamk_f32 v115, v115, 0x3a800000, v110
	s_waitcnt lgkmcnt(1)
	v_add_f32_e32 v116, v116, v118
	v_mul_f32_e32 v118, 0x4f800000, v115
	v_cmp_gt_f32_e32 vcc, s48, v115
	s_waitcnt lgkmcnt(0)
	v_add_f32_e32 v114, v114, v120
	ds_bpermute_b32 v119, v106, v117
	v_cndmask_b32_e32 v115, v115, v118, vcc
	ds_bpermute_b32 v120, v106, v114
	v_sqrt_f32_e32 v118, v115
	s_waitcnt lgkmcnt(1)
	v_add_f32_e32 v117, v117, v119
	ds_bpermute_b32 v119, v105, v117
	v_add_u32_e32 v122, -1, v118
	s_waitcnt lgkmcnt(1)
	v_add_f32_e32 v114, v114, v120
	v_fma_f32 v123, -v122, v118, v115
	ds_bpermute_b32 v120, v105, v114
	v_cmp_ge_f32_e64 s[4:5], 0, v123
	v_add_u32_e32 v123, 1, v118
	s_waitcnt lgkmcnt(1)
	v_add_f32_e32 v117, v117, v119
	v_cndmask_b32_e64 v122, v118, v122, s[4:5]
	v_fma_f32 v118, -v123, v118, v115
	v_cmp_lt_f32_e64 s[4:5], 0, v118
	ds_bpermute_b32 v119, v104, v116
	s_waitcnt lgkmcnt(1)
	v_add_f32_e32 v114, v114, v120
	v_cndmask_b32_e64 v118, v122, v123, s[4:5]
	v_mul_f32_e32 v122, 0x37800000, v118
	v_cndmask_b32_e32 v118, v118, v122, vcc
	v_cmp_class_f32_e32 vcc, v115, v111
	ds_bpermute_b32 v121, v104, v114
	ds_bpermute_b32 v120, v104, v117
	v_cndmask_b32_e32 v115, v118, v115, vcc
	v_div_scale_f32 v118, s[4:5], v115, v115, 1.0
	v_rcp_f32_e32 v122, v118
	s_waitcnt lgkmcnt(2)
	v_add_f32_e32 v116, v116, v119
	v_fmamk_f32 v116, v116, 0x3a800000, v110
	s_waitcnt lgkmcnt(1)
	v_add_f32_e32 v119, v114, v121
	v_mul_f32_e32 v121, 0x4f800000, v116
	v_cmp_gt_f32_e64 s[4:5], s48, v116
	v_fma_f32 v114, -v118, v122, 1.0
	v_fmac_f32_e32 v122, v114, v122
	v_cndmask_b32_e64 v116, v116, v121, s[4:5]
	v_div_scale_f32 v114, vcc, 1.0, v115, 1.0
	v_sqrt_f32_e32 v121, v116
	s_waitcnt lgkmcnt(0)
	v_add_f32_e32 v117, v117, v120
	v_mul_f32_e32 v120, v114, v122
	v_fma_f32 v123, -v118, v120, v114
	v_fmac_f32_e32 v120, v123, v122
	v_fma_f32 v114, -v118, v120, v114
	v_add_u32_e32 v118, -1, v121
	v_fma_f32 v123, -v118, v121, v116
	v_cmp_ge_f32_e64 s[6:7], 0, v123
	v_add_u32_e32 v123, 1, v121
	v_fmamk_f32 v117, v117, 0x3a800000, v110
	v_cndmask_b32_e64 v118, v121, v118, s[6:7]
	v_fma_f32 v121, -v123, v121, v116
	v_cmp_lt_f32_e64 s[6:7], 0, v121
	v_div_fmas_f32 v114, v114, v122, v120
	v_mul_f32_e32 v122, 0x4f800000, v117
	v_cndmask_b32_e64 v118, v118, v123, s[6:7]
	v_mul_f32_e32 v121, 0x37800000, v118
	v_cndmask_b32_e64 v118, v118, v121, s[4:5]
	v_cmp_class_f32_e64 s[4:5], v116, v111
	v_div_fixup_f32 v114, v114, v115, 1.0
	v_fmamk_f32 v119, v119, 0x3a800000, v110
	v_cndmask_b32_e64 v116, v118, v116, s[4:5]
	v_div_scale_f32 v118, s[4:5], v116, v116, 1.0
	v_rcp_f32_e32 v121, v118
	v_cmp_gt_f32_e64 s[4:5], s48, v117
	v_fma_f32 v115, -v118, v121, 1.0
	s_nop 0
	v_cndmask_b32_e64 v117, v117, v122, s[4:5]
	v_fmac_f32_e32 v121, v115, v121
	v_div_scale_f32 v115, vcc, 1.0, v116, 1.0
	v_sqrt_f32_e32 v122, v117
	v_mul_f32_e32 v120, v115, v121
	v_fma_f32 v123, -v118, v120, v115
	v_fmac_f32_e32 v120, v123, v121
	v_fma_f32 v115, -v118, v120, v115
	v_add_u32_e32 v118, -1, v122
	v_fma_f32 v123, -v118, v122, v117
	v_cmp_ge_f32_e64 s[6:7], 0, v123
	v_add_u32_e32 v123, 1, v122
	v_div_fmas_f32 v115, v115, v121, v120
	v_cndmask_b32_e64 v118, v122, v118, s[6:7]
	v_fma_f32 v122, -v123, v122, v117
	v_cmp_lt_f32_e64 s[6:7], 0, v122
	v_mul_f32_e32 v121, 0x4f800000, v119
	v_div_fixup_f32 v116, v115, v116, 1.0
	v_cndmask_b32_e64 v118, v118, v123, s[6:7]
	v_mul_f32_e32 v122, 0x37800000, v118
	v_cndmask_b32_e64 v118, v118, v122, s[4:5]
	v_cmp_class_f32_e64 s[4:5], v117, v111
	s_nop 1
	v_cndmask_b32_e64 v117, v118, v117, s[4:5]
	v_div_scale_f32 v118, s[4:5], v117, v117, 1.0
	v_rcp_f32_e32 v122, v118
	v_cmp_gt_f32_e64 s[4:5], s48, v119
	v_fma_f32 v115, -v118, v122, 1.0
	s_nop 0
	v_cndmask_b32_e64 v119, v119, v121, s[4:5]
	v_fmac_f32_e32 v122, v115, v122
	v_div_scale_f32 v115, vcc, 1.0, v117, 1.0
	v_sqrt_f32_e32 v121, v119
	v_mul_f32_e32 v120, v115, v122
	v_fma_f32 v123, -v118, v120, v115
	v_fmac_f32_e32 v120, v123, v122
	v_fma_f32 v115, -v118, v120, v115
	v_add_u32_e32 v118, -1, v121
	v_fma_f32 v123, -v118, v121, v119
	v_cmp_ge_f32_e64 s[6:7], 0, v123
	v_add_u32_e32 v123, 1, v121
	v_div_fmas_f32 v115, v115, v122, v120
	v_cndmask_b32_e64 v118, v121, v118, s[6:7]
	v_fma_f32 v121, -v123, v121, v119
	v_cmp_lt_f32_e64 s[6:7], 0, v121
	s_nop 1
	v_cndmask_b32_e64 v118, v118, v123, s[6:7]
	v_mul_f32_e32 v121, 0x37800000, v118
	v_cndmask_b32_e64 v118, v118, v121, s[4:5]
	v_cmp_class_f32_e64 s[4:5], v119, v111
	s_nop 1
	v_cndmask_b32_e64 v119, v118, v119, s[4:5]
	v_div_scale_f32 v121, s[4:5], v119, v119, 1.0
	v_rcp_f32_e32 v123, v121
	v_div_fixup_f32 v118, v115, v117, 1.0
	s_lshl_b64 s[4:5], s[42:43], 10
	v_pk_mul_f32 v[60:61], v[60:61], v[118:119] op_sel_hi:[1,0]
	v_fma_f32 v115, -v121, v123, 1.0
	v_fmac_f32_e32 v123, v115, v123
	v_div_scale_f32 v115, vcc, 1.0, v119, 1.0
	v_mul_f32_e32 v117, v115, v123
	v_fma_f32 v120, -v121, v117, v115
	v_fmac_f32_e32 v117, v120, v123
	v_fma_f32 v115, -v121, v117, v115
	v_div_fmas_f32 v115, v115, v123, v117
	v_pk_mul_f32 v[92:93], v[92:93], v[114:115] op_sel_hi:[1,0]
	v_pk_mul_f32 v[88:89], v[88:89], v[114:115] op_sel_hi:[1,0]
	v_pk_fma_f32 v[92:93], v[16:17], v[92:93], v[0:1]
	v_pk_mul_f32 v[94:95], v[94:95], v[114:115] op_sel_hi:[1,0]
	v_pk_mul_f32 v[90:91], v[90:91], v[114:115] op_sel_hi:[1,0]
	v_pk_fma_f32 v[88:89], v[20:21], v[88:89], v[4:5]
	v_pk_mul_f32 v[84:85], v[84:85], v[114:115] op_sel_hi:[1,0]
	v_pk_mul_f32 v[86:87], v[86:87], v[114:115] op_sel_hi:[1,0]
	v_pk_mul_f32 v[80:81], v[80:81], v[114:115] op_sel_hi:[1,0]
	v_pk_mul_f32 v[82:83], v[82:83], v[114:115] op_sel_hi:[1,0]
	v_med3_f32 v114, v92, s49, v113
	v_med3_f32 v93, v93, s49, v113
	v_mov_b32_e32 v92, 0
	v_cvt_pk_fp8_f32 v92, v114, v93
	v_med3_f32 v88, v88, s49, v113
	v_med3_f32 v89, v89, s49, v113
	v_mov_b32_e32 v93, 0
	v_cvt_pk_fp8_f32 v93, v88, v89
	v_pk_fma_f32 v[90:91], v[22:23], v[90:91], v[6:7]
	v_pk_fma_f32 v[84:85], v[24:25], v[84:85], v[8:9]
	v_med3_f32 v88, v90, s49, v113
	v_med3_f32 v89, v91, s49, v113
	v_pk_fma_f32 v[80:81], v[28:29], v[80:81], v[12:13]
	v_cvt_pk_fp8_f32 v93, v88, v89 op_sel:[0,0,1]
	v_med3_f32 v88, v84, s49, v113
	v_med3_f32 v85, v85, s49, v113
	v_mov_b32_e32 v84, 0
	v_cvt_pk_fp8_f32 v84, v88, v85
	v_med3_f32 v80, v80, s49, v113
	v_med3_f32 v81, v81, s49, v113
	v_mov_b32_e32 v85, 0
	v_cvt_pk_fp8_f32 v85, v80, v81
	v_pk_fma_f32 v[94:95], v[18:19], v[94:95], v[2:3]
	v_pk_fma_f32 v[86:87], v[26:27], v[86:87], v[10:11]
	v_pk_fma_f32 v[82:83], v[30:31], v[82:83], v[14:15]
	v_med3_f32 v94, v94, s49, v113
	v_med3_f32 v95, v95, s49, v113
	v_cvt_pk_fp8_f32 v92, v94, v95 op_sel:[0,0,1]
	v_med3_f32 v86, v86, s49, v113
	v_med3_f32 v87, v87, s49, v113
	v_med3_f32 v80, v82, s49, v113
	v_med3_f32 v81, v83, s49, v113
	v_cvt_pk_fp8_f32 v84, v86, v87 op_sel:[0,0,1]
	v_cvt_pk_fp8_f32 v85, v80, v81 op_sel:[0,0,1]
	v_pk_mul_f32 v[76:77], v[76:77], v[116:117] op_sel_hi:[1,0]
	v_lshl_add_u64 v[80:81], v[98:99], 0, s[4:5]
	v_pk_fma_f32 v[76:77], v[16:17], v[76:77], v[0:1]
	v_pk_mul_f32 v[72:73], v[72:73], v[116:117] op_sel_hi:[1,0]
	global_store_dwordx2 v[80:81], v[92:93], off
	global_store_dwordx2 v[80:81], v[84:85], off offset:512
	v_pk_fma_f32 v[72:73], v[20:21], v[72:73], v[4:5]
	v_med3_f32 v80, v76, s49, v113
	v_med3_f32 v77, v77, s49, v113
	v_mov_b32_e32 v76, 0
	v_cvt_pk_fp8_f32 v76, v80, v77
	v_med3_f32 v72, v72, s49, v113
	v_med3_f32 v73, v73, s49, v113
	v_mov_b32_e32 v77, 0
	v_cvt_pk_fp8_f32 v77, v72, v73
	v_pk_mul_f32 v[74:75], v[74:75], v[116:117] op_sel_hi:[1,0]
	v_pk_mul_f32 v[68:69], v[68:69], v[116:117] op_sel_hi:[1,0]
	v_pk_fma_f32 v[74:75], v[22:23], v[74:75], v[6:7]
	v_pk_fma_f32 v[68:69], v[24:25], v[68:69], v[8:9]
	v_pk_mul_f32 v[64:65], v[64:65], v[116:117] op_sel_hi:[1,0]
	v_med3_f32 v72, v74, s49, v113
	v_med3_f32 v73, v75, s49, v113
	v_pk_fma_f32 v[64:65], v[28:29], v[64:65], v[12:13]
	v_cvt_pk_fp8_f32 v77, v72, v73 op_sel:[0,0,1]
	v_med3_f32 v72, v68, s49, v113
	v_med3_f32 v69, v69, s49, v113
	v_mov_b32_e32 v68, 0
	v_cvt_pk_fp8_f32 v68, v72, v69
	v_med3_f32 v64, v64, s49, v113
	v_med3_f32 v65, v65, s49, v113
	v_mov_b32_e32 v69, 0
	v_pk_mul_f32 v[78:79], v[78:79], v[116:117] op_sel_hi:[1,0]
	v_cvt_pk_fp8_f32 v69, v64, v65
	v_pk_fma_f32 v[78:79], v[18:19], v[78:79], v[2:3]
	v_pk_mul_f32 v[70:71], v[70:71], v[116:117] op_sel_hi:[1,0]
	v_pk_mul_f32 v[66:67], v[66:67], v[116:117] op_sel_hi:[1,0]
	v_pk_fma_f32 v[70:71], v[26:27], v[70:71], v[10:11]
	v_pk_fma_f32 v[66:67], v[30:31], v[66:67], v[14:15]
	v_med3_f32 v78, v78, s49, v113
	v_med3_f32 v79, v79, s49, v113
	s_add_i32 s4, s42, 1
	v_cvt_pk_fp8_f32 v76, v78, v79 op_sel:[0,0,1]
	v_med3_f32 v70, v70, s49, v113
	v_med3_f32 v71, v71, s49, v113
	v_med3_f32 v64, v66, s49, v113
	v_med3_f32 v65, v67, s49, v113
	s_ashr_i32 s5, s4, 31
	v_cvt_pk_fp8_f32 v68, v70, v71 op_sel:[0,0,1]
	v_cvt_pk_fp8_f32 v69, v64, v65 op_sel:[0,0,1]
	s_lshl_b64 s[4:5], s[4:5], 10
	v_lshl_add_u64 v[64:65], v[98:99], 0, s[4:5]
	v_pk_fma_f32 v[60:61], v[16:17], v[60:61], v[0:1]
	v_pk_mul_f32 v[56:57], v[56:57], v[118:119] op_sel_hi:[1,0]
	global_store_dwordx2 v[64:65], v[76:77], off
	global_store_dwordx2 v[64:65], v[68:69], off offset:512
	v_pk_fma_f32 v[56:57], v[20:21], v[56:57], v[4:5]
	v_med3_f32 v64, v60, s49, v113
	v_med3_f32 v61, v61, s49, v113
	v_mov_b32_e32 v60, 0
	v_cvt_pk_fp8_f32 v60, v64, v61
	v_med3_f32 v56, v56, s49, v113
	v_med3_f32 v57, v57, s49, v113
	v_mov_b32_e32 v61, 0
	v_cvt_pk_fp8_f32 v61, v56, v57
	v_pk_mul_f32 v[58:59], v[58:59], v[118:119] op_sel_hi:[1,0]
	v_pk_mul_f32 v[52:53], v[52:53], v[118:119] op_sel_hi:[1,0]
	v_pk_fma_f32 v[58:59], v[22:23], v[58:59], v[6:7]
	v_div_fixup_f32 v120, v115, v119, 1.0
	v_pk_fma_f32 v[52:53], v[24:25], v[52:53], v[8:9]
	v_pk_mul_f32 v[48:49], v[48:49], v[118:119] op_sel_hi:[1,0]
	v_med3_f32 v56, v58, s49, v113
	v_med3_f32 v57, v59, s49, v113
	v_pk_mul_f32 v[50:51], v[50:51], v[118:119] op_sel_hi:[1,0]
	v_pk_fma_f32 v[48:49], v[28:29], v[48:49], v[12:13]
	v_cvt_pk_fp8_f32 v61, v56, v57 op_sel:[0,0,1]
	v_med3_f32 v56, v52, s49, v113
	v_med3_f32 v53, v53, s49, v113
	v_mov_b32_e32 v52, 0
	v_pk_mul_f32 v[44:45], v[44:45], v[120:121] op_sel_hi:[1,0]
	v_pk_fma_f32 v[50:51], v[30:31], v[50:51], v[14:15]
	v_cvt_pk_fp8_f32 v52, v56, v53
	v_med3_f32 v48, v48, s49, v113
	v_med3_f32 v49, v49, s49, v113
	v_mov_b32_e32 v53, 0
	v_pk_fma_f32 v[44:45], v[16:17], v[44:45], v[0:1]
	v_pk_mul_f32 v[40:41], v[40:41], v[120:121] op_sel_hi:[1,0]
	v_cvt_pk_fp8_f32 v53, v48, v49
	v_med3_f32 v48, v50, s49, v113
	v_pk_fma_f32 v[40:41], v[20:21], v[40:41], v[4:5]
	v_med3_f32 v50, v44, s49, v113
	v_med3_f32 v45, v45, s49, v113
	v_mov_b32_e32 v44, 0
	v_cvt_pk_fp8_f32 v44, v50, v45
	v_med3_f32 v40, v40, s49, v113
	v_med3_f32 v41, v41, s49, v113
	v_mov_b32_e32 v45, 0
	v_cvt_pk_fp8_f32 v45, v40, v41
	v_pk_mul_f32 v[42:43], v[42:43], v[120:121] op_sel_hi:[1,0]
	v_pk_mul_f32 v[36:37], v[36:37], v[120:121] op_sel_hi:[1,0]
	v_pk_fma_f32 v[42:43], v[22:23], v[42:43], v[6:7]
	v_pk_fma_f32 v[36:37], v[24:25], v[36:37], v[8:9]
	v_pk_mul_f32 v[32:33], v[32:33], v[120:121] op_sel_hi:[1,0]
	v_med3_f32 v40, v42, s49, v113
	v_med3_f32 v41, v43, s49, v113
	v_pk_fma_f32 v[32:33], v[28:29], v[32:33], v[12:13]
	v_cvt_pk_fp8_f32 v45, v40, v41 op_sel:[0,0,1]
	v_med3_f32 v40, v36, s49, v113
	v_med3_f32 v37, v37, s49, v113
	v_mov_b32_e32 v36, 0
	v_cvt_pk_fp8_f32 v36, v40, v37
	v_med3_f32 v32, v32, s49, v113
	v_med3_f32 v33, v33, s49, v113
	v_mov_b32_e32 v37, 0
	v_pk_mul_f32 v[62:63], v[62:63], v[118:119] op_sel_hi:[1,0]
	v_cvt_pk_fp8_f32 v37, v32, v33
	v_pk_fma_f32 v[62:63], v[18:19], v[62:63], v[2:3]
	v_pk_mul_f32 v[54:55], v[54:55], v[118:119] op_sel_hi:[1,0]
	s_add_i32 s4, s42, 2
	v_pk_mul_f32 v[46:47], v[46:47], v[120:121] op_sel_hi:[1,0]
	v_pk_mul_f32 v[38:39], v[38:39], v[120:121] op_sel_hi:[1,0]
	v_pk_mul_f32 v[34:35], v[34:35], v[120:121] op_sel_hi:[1,0]
	v_pk_fma_f32 v[54:55], v[26:27], v[54:55], v[10:11]
	s_ashr_i32 s5, s4, 31
	v_med3_f32 v62, v62, s49, v113
	v_med3_f32 v63, v63, s49, v113
	v_pk_fma_f32 v[46:47], v[18:19], v[46:47], v[2:3]
	v_pk_fma_f32 v[38:39], v[26:27], v[38:39], v[10:11]
	v_pk_fma_f32 v[34:35], v[30:31], v[34:35], v[14:15]
	v_cvt_pk_fp8_f32 v60, v62, v63 op_sel:[0,0,1]
	v_med3_f32 v54, v54, s49, v113
	v_med3_f32 v55, v55, s49, v113
	v_med3_f32 v49, v51, s49, v113
	s_lshl_b64 s[4:5], s[4:5], 10
	v_med3_f32 v46, v46, s49, v113
	v_med3_f32 v47, v47, s49, v113
	v_med3_f32 v38, v38, s49, v113
	v_med3_f32 v39, v39, s49, v113
	v_med3_f32 v32, v34, s49, v113
	v_med3_f32 v33, v35, s49, v113
	v_cvt_pk_fp8_f32 v52, v54, v55 op_sel:[0,0,1]
	v_cvt_pk_fp8_f32 v53, v48, v49 op_sel:[0,0,1]
	v_lshl_add_u64 v[48:49], v[98:99], 0, s[4:5]
	s_add_i32 s4, s42, 3
	v_cvt_pk_fp8_f32 v44, v46, v47 op_sel:[0,0,1]
	v_cvt_pk_fp8_f32 v36, v38, v39 op_sel:[0,0,1]
	v_cvt_pk_fp8_f32 v37, v32, v33 op_sel:[0,0,1]
	s_ashr_i32 s5, s4, 31
	s_lshl_b64 s[4:5], s[4:5], 10
	global_store_dwordx2 v[48:49], v[60:61], off
	global_store_dwordx2 v[48:49], v[52:53], off offset:512
	v_lshl_add_u64 v[48:49], v[98:99], 0, s[4:5]
	s_cmp_lg_u32 s50, 24
	global_store_dwordx2 v[48:49], v[44:45], off
	global_store_dwordx2 v[48:49], v[36:37], off offset:512
	s_cbranch_scc0 .LBB0_75

.LBB0_72:
	s_mul_i32 s6, s4, 0x6000
	s_mul_hi_i32 s5, s4, 0x6000
	s_add_u32 s6, s45, s6
	s_addc_u32 s7, s46, s5
	s_add_u32 s52, s6, 0x1000
	s_addc_u32 s53, s7, 0
	global_load_dwordx4 v[16:19], v112, s[52:53]
	global_load_dwordx4 v[20:23], v112, s[52:53] offset:16
	global_load_dwordx4 v[24:27], v97, s[52:53]
	global_load_dwordx4 v[28:31], v97, s[52:53] offset:16
	global_load_dwordx4 v[32:35], v[100:101], off
	global_load_dwordx4 v[36:39], v[100:101], off offset:16
	global_load_dwordx4 v[40:43], v[100:101], off offset:2048
	global_load_dwordx4 v[44:47], v[100:101], off offset:2064
	global_load_dwordx4 v[4:7], v112, s[6:7] offset:16
	global_load_dwordx4 v[0:3], v112, s[6:7]
	global_load_dwordx4 v[12:15], v112, s[6:7] offset:2064
	global_load_dwordx4 v[8:11], v112, s[6:7] offset:2048
	s_mov_b32 s51, s4
	s_waitcnt vmcnt(11)
	v_pk_add_f32 v[18:19], v[18:19], 1.0 op_sel_hi:[1,0]
	v_pk_add_f32 v[16:17], v[16:17], 1.0 op_sel_hi:[1,0]
	s_waitcnt vmcnt(10)
	v_pk_add_f32 v[22:23], v[22:23], 1.0 op_sel_hi:[1,0]
	v_pk_add_f32 v[20:21], v[20:21], 1.0 op_sel_hi:[1,0]
	s_waitcnt vmcnt(9)
	v_pk_add_f32 v[26:27], v[26:27], 1.0 op_sel_hi:[1,0]
	v_pk_add_f32 v[24:25], v[24:25], 1.0 op_sel_hi:[1,0]
	s_waitcnt vmcnt(8)
	v_pk_add_f32 v[30:31], v[30:31], 1.0 op_sel_hi:[1,0]
	v_pk_add_f32 v[28:29], v[28:29], 1.0 op_sel_hi:[1,0]
	s_waitcnt vmcnt(7)
	v_pk_mul_f32 v[18:19], v[34:35], v[18:19]
	v_pk_mul_f32 v[16:17], v[32:33], v[16:17]
	s_waitcnt vmcnt(6)
	v_pk_mul_f32 v[22:23], v[38:39], v[22:23]
	v_pk_mul_f32 v[20:21], v[36:37], v[20:21]
	s_waitcnt vmcnt(5)
	v_pk_mul_f32 v[26:27], v[42:43], v[26:27]
	v_pk_mul_f32 v[24:25], v[40:41], v[24:25]
	s_waitcnt vmcnt(4)
	v_pk_mul_f32 v[30:31], v[46:47], v[30:31]
	v_pk_mul_f32 v[28:29], v[44:45], v[28:29]
	s_waitcnt vmcnt(0)
	s_cmpk_gt_i32 s42, 0x7fff
	s_mov_b64 s[6:7], -1
	s_cbranch_scc0 .LBB0_71
